# P1 and P7 modulation staging: both loop iterations' loads issued up front (one round trip instead of two)
# baseline (speedup 1.0000x reference)
.LBB0_246:
	v_lshlrev_b32_e32 v6, 2, v2
	v_lshlrev_b32_e32 v7, 2, v3
	v_add_u32_e32 v8, 0x1000, v6
	v_add_u32_e32 v9, 0x1000, v7
	global_load_dword v10, v6, s[50:51]
	global_load_dword v11, v7, s[50:51]
	global_load_dword v16, v8, s[50:51]
	global_load_dword v17, v9, s[50:51]
	global_load_dword v12, v6, s[76:77]
	global_load_dword v13, v7, s[76:77]
	global_load_dword v18, v8, s[76:77]
	global_load_dword v19, v9, s[76:77]
	global_load_dword v5, v6, s[52:53]
	global_load_dword v14, v7, s[52:53]
	global_load_dword v20, v8, s[52:53]
	global_load_dword v21, v9, s[52:53]
	v_add_u32_e32 v3, 0x800, v3
	v_add_u32_e32 v2, 0x800, v2
	v_mov_b32_e32 v0, 0
	v_add_u32_e32 v15, 0x1000, v4
	s_waitcnt vmcnt(4)
	v_pk_add_f32 v[10:11], v[10:11], 1.0 op_sel_hi:[1,0]
	v_pk_add_f32 v[16:17], v[16:17], 1.0 op_sel_hi:[1,0]
	v_pk_mul_f32 v[10:11], v[10:11], v[12:13]
	v_pk_mul_f32 v[16:17], v[16:17], v[18:19]
	ds_write2st64_b32 v4, v10, v11 offset1:8
	ds_write2st64_b32 v15, v16, v17 offset1:8
	s_waitcnt vmcnt(0)
	ds_write2st64_b32 v4, v5, v14 offset0:32 offset1:40
	ds_write2st64_b32 v15, v20, v21 offset0:32 offset1:40
	v_add_u32_e32 v4, 0x2000, v4
	s_or_b64 exec, exec, s[54:55]
	s_mov_b64 s[12:13], 0
	s_and_saveexec_b64 s[50:51], s[44:45]
	s_mov_b64 s[12:13], exec
	v_lshlrev_b32_e32 v3, 2, v84
	s_or_b64 exec, exec, s[50:51]
	s_orn2_b64 s[12:13], s[12:13], exec
	v_mov_b32_e32 v2, v84

.LBB0_812:
	v_ashrrev_i32_e32 v7, 31, v3
	v_mov_b32_e32 v6, v3
	v_ashrrev_i32_e32 v9, 31, v2
	v_mov_b32_e32 v8, v2
	v_lshlrev_b64 v[8:9], 2, v[8:9]
	v_lshlrev_b64 v[6:7], 2, v[6:7]
	v_lshl_add_u64 v[10:11], s[84:85], 0, v[8:9]
	v_lshl_add_u64 v[14:15], s[52:53], 0, v[8:9]
	v_lshl_add_u64 v[16:17], s[52:53], 0, v[6:7]
	v_lshl_add_u64 v[18:19], s[50:51], 0, v[8:9]
	v_lshl_add_u64 v[20:21], s[50:51], 0, v[6:7]
	v_lshl_add_u64 v[22:23], s[56:57], 0, v[8:9]
	v_lshl_add_u64 v[24:25], s[56:57], 0, v[6:7]
	v_lshl_add_u64 v[26:27], s[54:55], 0, v[8:9]
	v_lshl_add_u64 v[28:29], s[54:55], 0, v[6:7]
	v_lshl_add_u64 v[30:31], s[60:61], 0, v[8:9]
	v_lshl_add_u64 v[32:33], s[60:61], 0, v[6:7]
	v_lshl_add_u64 v[34:35], s[58:59], 0, v[8:9]
	v_lshl_add_u64 v[36:37], s[58:59], 0, v[6:7]
	v_lshl_add_u64 v[38:39], s[64:65], 0, v[8:9]
	v_lshl_add_u64 v[40:41], s[64:65], 0, v[6:7]
	v_lshl_add_u64 v[12:13], s[84:85], 0, v[6:7]
	v_lshl_add_u64 v[42:43], s[62:63], 0, v[8:9]
	v_lshl_add_u64 v[44:45], s[62:63], 0, v[6:7]
	v_lshl_add_u64 v[46:47], s[68:69], 0, v[8:9]
	v_lshl_add_u64 v[48:49], s[68:69], 0, v[6:7]
	v_lshl_add_u64 v[50:51], s[66:67], 0, v[8:9]
	v_lshl_add_u64 v[52:53], s[66:67], 0, v[6:7]
	v_lshl_add_u64 v[54:55], s[72:73], 0, v[8:9]
	v_lshl_add_u64 v[56:57], s[72:73], 0, v[6:7]
	v_lshl_add_u64 v[58:59], s[70:71], 0, v[8:9]
	v_lshl_add_u64 v[60:61], s[70:71], 0, v[6:7]
	v_lshl_add_u64 v[66:67], s[42:43], 0, v[8:9]
	v_lshl_add_u64 v[68:69], s[42:43], 0, v[6:7]
	v_lshl_add_u64 v[74:75], s[38:39], 0, v[8:9]
	v_add_co_u32_e32 v78, vcc, 0x2000, v10
	global_load_dword v14, v[14:15], off
	s_nop 0
	global_load_dword v15, v[16:17], off
	s_nop 0
	global_load_dword v16, v[18:19], off
	global_load_dword v17, v[20:21], off
	s_nop 0
	global_load_dword v18, v[22:23], off
	global_load_dword v19, v[24:25], off
	global_load_dword v20, v[26:27], off
	global_load_dword v21, v[28:29], off
	s_nop 0
	global_load_dword v22, v[30:31], off
	global_load_dword v23, v[32:33], off
	global_load_dword v24, v[34:35], off
	global_load_dword v25, v[36:37], off
	global_load_dword v26, v[38:39], off
	global_load_dword v27, v[40:41], off
	global_load_dword v28, v[42:43], off
	global_load_dword v29, v[44:45], off
	global_load_dword v30, v[10:11], off
	global_load_dword v31, v[12:13], off
	global_load_dword v32, v[66:67], off
	global_load_dword v33, v[68:69], off
	s_nop 0
	global_load_dword v10, v[74:75], off
	global_load_dword v34, v[46:47], off
	global_load_dword v35, v[48:49], off
	global_load_dword v36, v[50:51], off
	global_load_dword v37, v[52:53], off
	global_load_dword v38, v[54:55], off
	global_load_dword v40, v[58:59], off
	global_load_dword v41, v[60:61], off
	global_load_dword v39, v[56:57], off
	s_mov_b64 s[0:1], vcc
	v_add_co_u32_e32 v12, vcc, 0x2000, v12
	v_lshl_add_u64 v[62:63], s[40:41], 0, v[8:9]
	v_lshl_add_u64 v[70:71], s[96:97], 0, v[8:9]
	v_lshl_add_u64 v[8:9], s[78:79], 0, v[8:9]
	v_addc_co_u32_e64 v79, s[0:1], 0, v11, s[0:1]
	v_addc_co_u32_e32 v13, vcc, 0, v13, vcc
	v_lshl_add_u64 v[64:65], s[40:41], 0, v[6:7]
	v_lshl_add_u64 v[72:73], s[96:97], 0, v[6:7]
	v_lshl_add_u64 v[76:77], s[38:39], 0, v[6:7]
	v_lshl_add_u64 v[6:7], s[78:79], 0, v[6:7]
	global_load_dword v42, v[78:79], off
	global_load_dword v43, v[12:13], off
	global_load_dword v11, v[76:77], off
	s_nop 0
	global_load_dword v12, v[62:63], off
	global_load_dword v44, v[70:71], off
	global_load_dword v45, v[72:73], off
	global_load_dword v13, v[64:65], off
	s_nop 0
	global_load_dword v8, v[8:9], off
	s_nop 0
	global_load_dword v9, v[6:7], off
	v_add_u32_e32 v236, 0x400, v2
	v_add_u32_e32 v237, 0x400, v3
	v_lshlrev_b32_e32 v236, 2, v236
	v_lshlrev_b32_e32 v237, 2, v237
	v_add_u32_e32 v238, 0x2000, v236
	v_add_u32_e32 v239, 0x2000, v237
	global_load_dword v178, v236, s[52:53]
	global_load_dword v179, v237, s[52:53]
	global_load_dword v180, v236, s[50:51]
	global_load_dword v181, v237, s[50:51]
	global_load_dword v182, v236, s[56:57]
	global_load_dword v183, v237, s[56:57]
	global_load_dword v184, v236, s[54:55]
	global_load_dword v185, v237, s[54:55]
	global_load_dword v186, v236, s[60:61]
	global_load_dword v187, v237, s[60:61]
	global_load_dword v188, v236, s[58:59]
	global_load_dword v189, v237, s[58:59]
	global_load_dword v190, v236, s[64:65]
	global_load_dword v191, v237, s[64:65]
	global_load_dword v192, v236, s[62:63]
	global_load_dword v193, v237, s[62:63]
	global_load_dword v194, v236, s[84:85]
	global_load_dword v195, v237, s[84:85]
	global_load_dword v196, v236, s[42:43]
	global_load_dword v197, v237, s[42:43]
	global_load_dword v174, v236, s[38:39]
	global_load_dword v198, v236, s[68:69]
	global_load_dword v199, v237, s[68:69]
	global_load_dword v200, v236, s[66:67]
	global_load_dword v201, v237, s[66:67]
	global_load_dword v224, v236, s[72:73]
	global_load_dword v226, v236, s[70:71]
	global_load_dword v227, v237, s[70:71]
	global_load_dword v225, v237, s[72:73]
	global_load_dword v228, v238, s[84:85]
	global_load_dword v229, v239, s[84:85]
	global_load_dword v175, v237, s[38:39]
	global_load_dword v176, v236, s[40:41]
	global_load_dword v230, v236, s[96:97]
	global_load_dword v231, v237, s[96:97]
	global_load_dword v177, v237, s[40:41]
	global_load_dword v172, v236, s[78:79]
	global_load_dword v173, v237, s[78:79]
	s_waitcnt vmcnt(58)
	v_pk_add_f32 v[6:7], v[30:31], v[16:17]
	s_nop 0
	v_pk_add_f32 v[6:7], v[6:7], v[20:21]
	s_waitcnt vmcnt(45)
	v_pk_add_f32 v[14:15], v[42:43], v[14:15]
	v_pk_add_f32 v[6:7], v[6:7], v[24:25]
	v_pk_add_f32 v[14:15], v[14:15], v[18:19]
	v_pk_add_f32 v[6:7], v[6:7], v[28:29]
	v_pk_add_f32 v[14:15], v[14:15], v[22:23]
	v_pk_add_f32 v[6:7], v[6:7], v[36:37]
	v_pk_add_f32 v[14:15], v[14:15], v[26:27]
	v_pk_add_f32 v[6:7], v[6:7], v[40:41]
	s_nop 0
	v_pk_add_f32 v[6:7], v[6:7], v[32:33]
	s_waitcnt vmcnt(44)
	v_pk_add_f32 v[6:7], v[6:7], v[10:11]
	v_pk_add_f32 v[10:11], v[14:15], v[34:35]
	ds_write2st64_b32 v4, v6, v7 offset0:32 offset1:40
	v_pk_add_f32 v[6:7], v[10:11], v[38:39]
	s_waitcnt vmcnt(40)
	v_pk_add_f32 v[6:7], v[6:7], v[12:13]
	s_nop 0
	v_pk_add_f32 v[6:7], v[6:7], v[44:45]
	s_nop 0
	v_pk_add_f32 v[6:7], v[6:7], 1.0 op_sel_hi:[1,0]
	s_waitcnt vmcnt(38)
	v_pk_mul_f32 v[6:7], v[6:7], v[8:9]
	ds_write2st64_b32 v4, v6, v7 offset1:8
	v_add_u32_e32 v4, 0x1000, v4
	s_waitcnt vmcnt(20)
	v_pk_add_f32 v[6:7], v[194:195], v[180:181]
	s_nop 0
	v_pk_add_f32 v[6:7], v[6:7], v[184:185]
	s_waitcnt vmcnt(7)
	v_pk_add_f32 v[178:179], v[228:229], v[178:179]
	v_pk_add_f32 v[6:7], v[6:7], v[188:189]
	v_pk_add_f32 v[178:179], v[178:179], v[182:183]
	v_pk_add_f32 v[6:7], v[6:7], v[192:193]
	v_pk_add_f32 v[178:179], v[178:179], v[186:187]
	v_pk_add_f32 v[6:7], v[6:7], v[200:201]
	v_pk_add_f32 v[178:179], v[178:179], v[190:191]
	v_pk_add_f32 v[6:7], v[6:7], v[226:227]
	s_nop 0
	v_pk_add_f32 v[6:7], v[6:7], v[196:197]
	s_waitcnt vmcnt(6)
	v_pk_add_f32 v[6:7], v[6:7], v[174:175]
	v_pk_add_f32 v[174:175], v[178:179], v[198:199]
	ds_write2st64_b32 v4, v6, v7 offset0:32 offset1:40
	v_pk_add_f32 v[6:7], v[174:175], v[224:225]
	s_waitcnt vmcnt(2)
	v_pk_add_f32 v[6:7], v[6:7], v[176:177]
	s_nop 0
	v_pk_add_f32 v[6:7], v[6:7], v[230:231]
	s_nop 0
	v_pk_add_f32 v[6:7], v[6:7], 1.0 op_sel_hi:[1,0]
	s_waitcnt vmcnt(0)
	v_pk_mul_f32 v[6:7], v[6:7], v[172:173]
	ds_write2st64_b32 v4, v6, v7 offset1:8
	v_add_u32_e32 v4, 0x1000, v4
	v_add_u32_e32 v3, 0x800, v3
	v_add_u32_e32 v2, 0x800, v2
	v_mov_b32_e32 v0, 0
	s_or_b64 exec, exec, s[46:47]
	s_mov_b64 s[0:1], 0
	s_mov_b64 s[12:13], exec
	v_readlane_b32 s38, v255, 43
	v_readlane_b32 s39, v255, 44
	s_and_b64 s[38:39], s[12:13], s[38:39]
	s_mov_b64 exec, s[38:39]
	s_mov_b64 s[0:1], exec
	v_lshlrev_b32_e32 v3, 2, v155
	s_or_b64 exec, exec, s[12:13]
	v_readlane_b32 s96, v255, 15
	v_readlane_b32 s90, v255, 17
	s_orn2_b64 s[0:1], s[0:1], exec
	v_mov_b32_e32 v2, v155
	s_mov_b32 s88, s96
	v_readlane_b32 s91, v255, 18
	v_readlane_b32 s39, v255, 51
	v_readlane_b32 s38, v255, 49
	v_readlane_b32 s40, v255, 48
	v_readlane_b32 s46, v255, 50
	v_readlane_b32 s41, v255, 47
	v_readlane_b32 s42, v255, 46
	v_readlane_b32 s43, v255, 45
	v_readlane_b32 s97, v255, 16
